# nt (non-temporal) hint on FF1's u stores so they do not evict the residual stream from the memory-side cache; otherwise v19
# baseline (speedup 1.0000x reference)
;     template <bool GATE> __device__ __forceinline__ void run(const f32x4 (&acc)[2][2][4][2], const Unit& u, int wr, int wc, int fr, int fq) const {
;     ...
;             for (int m = 0; m < 4; ++m) rsc[ai][m] = (MODE == EP_RELU2) ? __builtin_amdgcn_rcpf(RS[row0 + ai * HALF + m * 16] * (1.0f / 2048.0f) + 1e-6f) : 1.0f;
; #pragma unroll
;         for (int ai = 0; ai < 2; ++ai)
; #pragma unroll
;             for (int m = 0; m < 4; ++m) { const size_t r = (size_t)(row0 + ai * HALF + m * 16); float ss = 0.f;
; #pragma unroll
;                 for (int bj = 0; bj < 2; ++bj) { const int c = col0 + bj * HALF; f32x4 v0 = acc[ai][bj][m][0], v1 = acc[ai][bj][m][1];
;                     if (MODE == EP_INPROJ) { if (gate) { v0 = sigmoid4(v0 + bv[bj][0]); v1 = sigmoid4(v1 + bv[bj][1]); } }
;                     if (MODE == EP_T1 || MODE == EP_MERGE) { f32x4 g0, g1; unpack8(*(const u32x4*)(Gt + r * ldg + c), g0, g1); v0 = v0 * g0; v1 = v1 * g1; }
;                     if (MODE == EP_MERGE) { f32x4 t0, t1; unpack8(*(const u32x4*)(T + r * ldt + c), t0, t1); v0 = v0 + t0; v1 = v1 + t1; }
;                     if (MODE == EP_RELU2) {
; #pragma unroll
;                         for (int i = 0; i < 4; ++i) { const float a = fmaxf(v0[i], 0.f), b = fmaxf(v1[i], 0.f); v0[i] = a * a * rsc[ai][m]; v1[i] = b * b * rsc[ai][m]; } }
;                     if (MODE == EP_RESID_N) { const float* xp = X + r * 2048 + c; float* op = XO + r * 2048 + c;
;                         const f32x4 y0 = *(const f32x4*)xp + v0, y1 = *(const f32x4*)(xp + 4) + v1; *(f32x4*)op = y0; *(f32x4*)(op + 4) = y1;
;                         ss += (y0[0] * y0[0] + y0[1] * y0[1]) + (y0[2] * y0[2] + y0[3] * y0[3]) + (y1[0] * y1[0] + y1[1] * y1[1]) + (y1[2] * y1[2] + y1[3] * y1[3]);
;                         v0 = y0 * bv[bj][0]; v1 = y1 * bv[bj][1]; }
;                     if (MODE == EP_RESID) { const float* xp = X + r * 2048 + c; float* op = XO + r * 2048 + c;
;                         const f32x4 x0 = *(const f32x4*)xp, x1 = *(const f32x4*)(xp + 4); *(f32x4*)op = x0 + v0; *(f32x4*)(op + 4) = x1 + v1; }
;                     else { u32x4 w; w.x = cvt_pk_bf16(v0[0], v0[1]); w.y = cvt_pk_bf16(v0[2], v0[3]); w.z = cvt_pk_bf16(v1[0], v1[1]); w.w = cvt_pk_bf16(v1[2], v1[3]);
;                         *(u32x4*)(O + r * ldc + c) = w; } }
.LBB0_775:
	v_lshl_add_u32 v148, s63, 8, v144
	v_or_b32_e32 v142, 16, v148
	v_ashrrev_i32_e32 v149, 31, v148
	v_ashrrev_i32_e32 v143, 31, v142
	v_lshl_add_u64 v[138:139], v[148:149], 2, s[12:13]
	v_lshl_add_u64 v[140:141], v[142:143], 2, s[12:13]
	global_load_dword v152, v[138:139], off
	global_load_dword v153, v[140:141], off
	v_or_b32_e32 v140, 32, v148
	v_ashrrev_i32_e32 v141, 31, v140
	v_lshl_add_u64 v[150:151], v[140:141], 2, s[12:13]
	global_load_dword v154, v[150:151], off
	global_load_dword v155, v[138:139], off offset:512
	global_load_dword v156, v[138:139], off offset:576
	global_load_dword v157, v[138:139], off offset:640
	global_load_dword v158, v[138:139], off offset:704
	v_or_b32_e32 v138, 48, v148
	v_ashrrev_i32_e32 v139, 31, v138
	v_lshl_add_u64 v[150:151], v[138:139], 2, s[12:13]
	global_load_dword v159, v[150:151], off
	v_max_f32_e32 v120, v120, v120
	v_max_f32_e32 v120, 0, v120
	v_mul_f32_e32 v164, v120, v120
	v_lshl_or_b32 v150, s62, 8, v146
	v_max_f32_e32 v124, v124, v124
	v_max_f32_e32 v121, v121, v121
	v_max_f32_e32 v125, v125, v125
	v_max_f32_e32 v126, v126, v126
	v_max_f32_e32 v122, v122, v122
	v_max_f32_e32 v127, v127, v127
	v_max_f32_e32 v116, v116, v116
	v_max_f32_e32 v112, v112, v112
	v_max_f32_e32 v117, v117, v117
	v_max_f32_e32 v113, v113, v113
	v_max_f32_e32 v124, 0, v124
	v_max_f32_e32 v121, 0, v121
	v_ashrrev_i32_e32 v151, 31, v150
	v_max_f32_e32 v123, v123, v123
	v_max_f32_e32 v125, 0, v125
	v_max_f32_e32 v126, 0, v126
	v_max_f32_e32 v122, 0, v122
	v_max_f32_e32 v127, 0, v127
	v_max_f32_e32 v160, 0, v116
	v_max_f32_e32 v161, 0, v112
	v_max_f32_e32 v162, 0, v117
	v_max_f32_e32 v163, 0, v113
	v_mul_f32_e32 v124, v124, v124
	v_mul_f32_e32 v165, v121, v121
	v_lshlrev_b64 v[112:113], 14, v[148:149]
	v_lshlrev_b64 v[116:117], 1, v[150:151]
	v_max_f32_e32 v123, 0, v123
	v_mul_f32_e32 v125, v125, v125
	v_mul_f32_e32 v126, v126, v126
	v_mul_f32_e32 v166, v122, v122
	v_mul_f32_e32 v127, v127, v127
	v_lshl_add_u64 v[112:113], s[4:5], 0, v[112:113]
	v_max_f32_e32 v114, v114, v114
	v_mul_f32_e32 v123, v123, v123
	v_lshl_add_u64 v[112:113], v[112:113], 0, v[116:117]
	v_max_f32_e32 v118, v118, v118
	v_max_f32_e32 v114, 0, v114
	v_max_f32_e32 v119, v119, v119
	v_max_f32_e32 v115, v115, v115
	v_max_f32_e32 v104, v104, v104
	v_max_f32_e32 v105, v105, v105
	v_max_f32_e32 v106, v106, v106
	v_max_f32_e32 v118, 0, v118
	v_mul_f32_e32 v114, v114, v114
	v_max_f32_e32 v119, 0, v119
	v_max_f32_e32 v115, 0, v115
	v_max_f32_e32 v104, 0, v104
	v_max_f32_e32 v105, 0, v105
	v_max_f32_e32 v106, 0, v106
	v_mul_f32_e32 v148, v160, v160
	v_mul_f32_e32 v149, v161, v161
	v_mul_f32_e32 v118, v118, v118
	v_mul_f32_e32 v119, v119, v119
	v_mul_f32_e32 v115, v115, v115
	v_mul_f32_e32 v104, v104, v104
	v_mul_f32_e32 v105, v105, v105
	v_mul_f32_e32 v106, v106, v106
	v_max_f32_e32 v108, v108, v108
	v_max_f32_e32 v108, 0, v108
	v_mul_f32_e32 v108, v108, v108
	v_max_f32_e32 v107, v107, v107
	v_max_f32_e32 v107, 0, v107
	v_max_f32_e32 v96, v96, v96
	v_mul_f32_e32 v107, v107, v107
	v_max_f32_e32 v96, 0, v96
	v_max_f32_e32 v97, v97, v97
	s_waitcnt vmcnt(0)
	v_fmamk_f32 v120, v152, 0x3a000000, v237
	v_rcp_f32_e32 v152, v120
	v_fmamk_f32 v121, v155, 0x3a000000, v237
	v_fmamk_f32 v153, v153, 0x3a000000, v237
	v_fmamk_f32 v150, v157, 0x3a000000, v237
	v_fmamk_f32 v122, v156, 0x3a000000, v237
	v_rcp_f32_e32 v156, v121
	v_rcp_f32_e32 v121, v150
	v_rcp_f32_e32 v150, v153
	v_mul_f32_e32 v124, v124, v152
	v_fmamk_f32 v151, v158, 0x3a000000, v237
	v_fmamk_f32 v154, v154, 0x3a000000, v237
	v_fmamk_f32 v155, v159, 0x3a000000, v237
	v_mul_f32_e32 v125, v125, v152
	v_mul_f32_e32 v126, v126, v152
	v_mul_f32_e32 v127, v127, v152
	v_cvt_pk_bf16_f32 v124, v124, v125
	v_rcp_f32_e32 v120, v151
	v_rcp_f32_e32 v151, v154
	v_rcp_f32_e32 v153, v155
	v_mul_f32_e32 v154, v164, v152
	v_mul_f32_e32 v155, v165, v152
	v_mul_f32_e32 v157, v166, v152
	v_mul_f32_e32 v123, v123, v152
	v_cvt_pk_bf16_f32 v125, v126, v127
	v_cvt_pk_bf16_f32 v126, v154, v155
	v_cvt_pk_bf16_f32 v127, v157, v123
	global_store_dwordx4 v[112:113], v[124:127], off nt
	v_mul_f32_e32 v123, v162, v162
	v_mul_f32_e32 v114, v114, v152
	v_mul_f32_e32 v124, v163, v163
	v_mul_f32_e32 v126, v124, v152
	v_mul_f32_e32 v148, v148, v152
	v_mul_f32_e32 v149, v149, v152
	v_mul_f32_e32 v123, v123, v152
	v_mul_f32_e32 v118, v118, v152
	v_mul_f32_e32 v119, v119, v152
	v_mul_f32_e32 v115, v115, v152
	v_cvt_pk_bf16_f32 v124, v148, v123
	v_cvt_pk_bf16_f32 v125, v118, v119
	v_cvt_pk_bf16_f32 v126, v149, v126
	v_cvt_pk_bf16_f32 v127, v114, v115
	v_mul_f32_e32 v114, v104, v150
	v_max_f32_e32 v104, v109, v109
	v_mul_f32_e32 v109, v105, v150
	v_max_f32_e32 v105, v110, v110
	v_mul_f32_e32 v110, v106, v150
	v_max_f32_e32 v106, v111, v111
	v_max_f32_e32 v104, 0, v104
	v_max_f32_e32 v105, 0, v105
	v_max_f32_e32 v106, 0, v106
	v_mul_f32_e32 v104, v104, v104
	v_mul_f32_e32 v105, v105, v105
	v_mul_f32_e32 v106, v106, v106
	v_mul_f32_e32 v108, v108, v150
	v_mul_f32_e32 v104, v104, v150
	v_mul_f32_e32 v105, v105, v150
	v_mul_f32_e32 v106, v106, v150
	global_store_dwordx4 v[112:113], v[124:127], off offset:256 nt
	v_cvt_pk_bf16_f32 v104, v108, v104
	v_cvt_pk_bf16_f32 v105, v105, v106
	v_cvt_pk_bf16_f32 v106, v114, v109
	v_lshlrev_b64 v[108:109], 14, v[142:143]
	v_lshl_add_u64 v[108:109], s[4:5], 0, v[108:109]
	v_max_f32_e32 v98, v98, v98
	v_mul_f32_e32 v107, v107, v150
	v_lshl_add_u64 v[108:109], v[108:109], 0, v[116:117]
	v_mul_f32_e32 v96, v96, v96
	v_max_f32_e32 v97, 0, v97
	v_max_f32_e32 v98, 0, v98
	v_cvt_pk_bf16_f32 v107, v110, v107
	global_store_dwordx4 v[108:109], v[104:107], off nt
	v_mul_f32_e32 v97, v97, v97
	v_mul_f32_e32 v98, v98, v98
;     template <bool GATE> __device__ __forceinline__ void run(const f32x4 (&acc)[2][2][4][2], const Unit& u, int wr, int wc, int fr, int fq) const {
;     ...
;             for (int m = 0; m < 4; ++m) rsc[ai][m] = (MODE == EP_RELU2) ? __builtin_amdgcn_rcpf(RS[row0 + ai * HALF + m * 16] * (1.0f / 2048.0f) + 1e-6f) : 1.0f;
; #pragma unroll
;         for (int ai = 0; ai < 2; ++ai)
; #pragma unroll
;             for (int m = 0; m < 4; ++m) { const size_t r = (size_t)(row0 + ai * HALF + m * 16); float ss = 0.f;
; #pragma unroll
;                 for (int bj = 0; bj < 2; ++bj) { const int c = col0 + bj * HALF; f32x4 v0 = acc[ai][bj][m][0], v1 = acc[ai][bj][m][1];
;                     if (MODE == EP_INPROJ) { if (gate) { v0 = sigmoid4(v0 + bv[bj][0]); v1 = sigmoid4(v1 + bv[bj][1]); } }
;                     if (MODE == EP_T1 || MODE == EP_MERGE) { f32x4 g0, g1; unpack8(*(const u32x4*)(Gt + r * ldg + c), g0, g1); v0 = v0 * g0; v1 = v1 * g1; }
;                     if (MODE == EP_MERGE) { f32x4 t0, t1; unpack8(*(const u32x4*)(T + r * ldt + c), t0, t1); v0 = v0 + t0; v1 = v1 + t1; }
;                     if (MODE == EP_RELU2) {
; #pragma unroll
;                         for (int i = 0; i < 4; ++i) { const float a = fmaxf(v0[i], 0.f), b = fmaxf(v1[i], 0.f); v0[i] = a * a * rsc[ai][m]; v1[i] = b * b * rsc[ai][m]; } }
;                     if (MODE == EP_RESID_N) { const float* xp = X + r * 2048 + c; float* op = XO + r * 2048 + c;
;                         const f32x4 y0 = *(const f32x4*)xp + v0, y1 = *(const f32x4*)(xp + 4) + v1; *(f32x4*)op = y0; *(f32x4*)(op + 4) = y1;
;                         ss += (y0[0] * y0[0] + y0[1] * y0[1]) + (y0[2] * y0[2] + y0[3] * y0[3]) + (y1[0] * y1[0] + y1[1] * y1[1]) + (y1[2] * y1[2] + y1[3] * y1[3]);
;                         v0 = y0 * bv[bj][0]; v1 = y1 * bv[bj][1]; }
;                     if (MODE == EP_RESID) { const float* xp = X + r * 2048 + c; float* op = XO + r * 2048 + c;
;                         const f32x4 x0 = *(const f32x4*)xp, x1 = *(const f32x4*)(xp + 4); *(f32x4*)op = x0 + v0; *(f32x4*)(op + 4) = x1 + v1; }
;                     else { u32x4 w; w.x = cvt_pk_bf16(v0[0], v0[1]); w.y = cvt_pk_bf16(v0[2], v0[3]); w.z = cvt_pk_bf16(v1[0], v1[1]); w.w = cvt_pk_bf16(v1[2], v1[3]);
;                         *(u32x4*)(O + r * ldc + c) = w; } }
	v_mul_f32_e32 v104, v96, v150
	v_max_f32_e32 v96, v101, v101
	v_max_f32_e32 v100, v100, v100
	v_max_f32_e32 v96, 0, v96
	v_mul_f32_e32 v101, v97, v150
	v_max_f32_e32 v97, v102, v102
	v_mul_f32_e32 v102, v98, v150
	v_max_f32_e32 v98, v103, v103
	v_max_f32_e32 v99, v99, v99
	v_max_f32_e32 v100, 0, v100
	v_mul_f32_e32 v96, v96, v96
	v_max_f32_e32 v97, 0, v97
	v_max_f32_e32 v98, 0, v98
	v_max_f32_e32 v99, 0, v99
	v_max_f32_e32 v88, v88, v88
	v_max_f32_e32 v89, v89, v89
	v_max_f32_e32 v90, v90, v90
	v_mul_f32_e32 v100, v100, v100
	v_mul_f32_e32 v96, v96, v150
	v_mul_f32_e32 v97, v97, v97
	v_mul_f32_e32 v98, v98, v98
	v_mul_f32_e32 v99, v99, v99
	v_max_f32_e32 v88, 0, v88
	v_max_f32_e32 v89, 0, v89
	v_max_f32_e32 v90, 0, v90
	v_mul_f32_e32 v100, v100, v150
	v_mul_f32_e32 v97, v97, v150
	v_mul_f32_e32 v98, v98, v150
	v_mul_f32_e32 v99, v99, v150
	v_cvt_pk_bf16_f32 v96, v100, v96
	v_mul_f32_e32 v88, v88, v88
	v_mul_f32_e32 v89, v89, v89
	v_mul_f32_e32 v90, v90, v90
	v_cvt_pk_bf16_f32 v97, v97, v98
	v_cvt_pk_bf16_f32 v98, v104, v101
	v_cvt_pk_bf16_f32 v99, v102, v99
	global_store_dwordx4 v[108:109], v[96:99], off offset:256 nt
	v_max_f32_e32 v92, v92, v92
	v_max_f32_e32 v92, 0, v92
	v_mul_f32_e32 v96, v88, v151
	v_max_f32_e32 v88, v93, v93
	v_mul_f32_e32 v93, v89, v151
	v_max_f32_e32 v89, v94, v94
	v_mul_f32_e32 v94, v90, v151
	v_max_f32_e32 v90, v95, v95
	v_max_f32_e32 v88, 0, v88
	v_max_f32_e32 v89, 0, v89
	v_max_f32_e32 v90, 0, v90
	v_mul_f32_e32 v92, v92, v92
	v_mul_f32_e32 v88, v88, v88
	v_mul_f32_e32 v89, v89, v89
	v_mul_f32_e32 v90, v90, v90
	v_mul_f32_e32 v92, v92, v151
	v_mul_f32_e32 v88, v88, v151
	v_mul_f32_e32 v89, v89, v151
	v_max_f32_e32 v91, v91, v91
	v_mul_f32_e32 v90, v90, v151
	v_max_f32_e32 v91, 0, v91
	v_cvt_pk_bf16_f32 v88, v92, v88
	v_cvt_pk_bf16_f32 v89, v89, v90
	v_cvt_pk_bf16_f32 v90, v96, v93
	v_lshlrev_b64 v[92:93], 14, v[140:141]
	v_max_f32_e32 v80, v80, v80
	v_mul_f32_e32 v91, v91, v91
	v_lshl_add_u64 v[92:93], s[4:5], 0, v[92:93]
	v_max_f32_e32 v80, 0, v80
	v_max_f32_e32 v81, v81, v81
	v_max_f32_e32 v82, v82, v82
	v_mul_f32_e32 v91, v91, v151
	v_lshl_add_u64 v[92:93], v[92:93], 0, v[116:117]
	v_mul_f32_e32 v80, v80, v80
	v_max_f32_e32 v81, 0, v81
	v_max_f32_e32 v82, 0, v82
	v_cvt_pk_bf16_f32 v91, v94, v91
	global_store_dwordx4 v[92:93], v[88:91], off nt
	v_mul_f32_e32 v81, v81, v81
	v_mul_f32_e32 v82, v82, v82
	v_mul_f32_e32 v88, v80, v151
	v_max_f32_e32 v80, v85, v85
	v_max_f32_e32 v84, v84, v84
	v_max_f32_e32 v80, 0, v80
	v_mul_f32_e32 v85, v81, v151
	v_max_f32_e32 v81, v86, v86
	v_mul_f32_e32 v86, v82, v151
	v_max_f32_e32 v82, v87, v87
	v_max_f32_e32 v83, v83, v83
	v_max_f32_e32 v84, 0, v84
	v_mul_f32_e32 v80, v80, v80
	v_max_f32_e32 v81, 0, v81
	v_max_f32_e32 v82, 0, v82
	v_max_f32_e32 v83, 0, v83
	v_max_f32_e32 v72, v72, v72
	v_max_f32_e32 v73, v73, v73
	v_max_f32_e32 v74, v74, v74
	v_mul_f32_e32 v84, v84, v84
	v_mul_f32_e32 v80, v80, v151
	v_mul_f32_e32 v81, v81, v81
	v_mul_f32_e32 v82, v82, v82
	v_mul_f32_e32 v83, v83, v83
	v_max_f32_e32 v72, 0, v72
	v_max_f32_e32 v73, 0, v73
	v_max_f32_e32 v74, 0, v74
	v_mul_f32_e32 v84, v84, v151
	v_mul_f32_e32 v81, v81, v151
	v_mul_f32_e32 v82, v82, v151
	v_mul_f32_e32 v83, v83, v151
	v_cvt_pk_bf16_f32 v80, v84, v80
	v_mul_f32_e32 v72, v72, v72
	v_mul_f32_e32 v73, v73, v73
	v_mul_f32_e32 v74, v74, v74
	v_cvt_pk_bf16_f32 v81, v81, v82
	v_cvt_pk_bf16_f32 v82, v88, v85
	v_cvt_pk_bf16_f32 v83, v86, v83
	global_store_dwordx4 v[92:93], v[80:83], off offset:256 nt
	v_max_f32_e32 v76, v76, v76
	v_max_f32_e32 v76, 0, v76
	v_mul_f32_e32 v80, v72, v153
	v_max_f32_e32 v72, v77, v77
	v_mul_f32_e32 v77, v73, v153
	v_max_f32_e32 v73, v78, v78
	v_mul_f32_e32 v78, v74, v153
	v_max_f32_e32 v74, v79, v79
	v_max_f32_e32 v72, 0, v72
	v_max_f32_e32 v73, 0, v73
	v_max_f32_e32 v74, 0, v74
	v_mul_f32_e32 v76, v76, v76
	v_mul_f32_e32 v72, v72, v72
	v_mul_f32_e32 v73, v73, v73
	v_mul_f32_e32 v74, v74, v74
	v_mul_f32_e32 v76, v76, v153
	v_mul_f32_e32 v72, v72, v153
	v_mul_f32_e32 v73, v73, v153
	v_max_f32_e32 v75, v75, v75
	v_mul_f32_e32 v74, v74, v153
	v_max_f32_e32 v75, 0, v75
	v_cvt_pk_bf16_f32 v72, v76, v72
	v_cvt_pk_bf16_f32 v73, v73, v74
	v_cvt_pk_bf16_f32 v74, v80, v77
	v_lshlrev_b64 v[76:77], 14, v[138:139]
	v_max_f32_e32 v64, v64, v64
	v_mul_f32_e32 v75, v75, v75
	v_lshl_add_u64 v[76:77], s[4:5], 0, v[76:77]
	v_max_f32_e32 v64, 0, v64
	v_max_f32_e32 v65, v65, v65
	v_max_f32_e32 v66, v66, v66
	v_mul_f32_e32 v75, v75, v153
	v_lshl_add_u64 v[76:77], v[76:77], 0, v[116:117]
	v_mul_f32_e32 v64, v64, v64
	v_max_f32_e32 v65, 0, v65
	v_max_f32_e32 v66, 0, v66
	v_cvt_pk_bf16_f32 v75, v78, v75
	global_store_dwordx4 v[76:77], v[72:75], off nt
	v_mul_f32_e32 v65, v65, v65
	v_mul_f32_e32 v66, v66, v66
	v_mul_f32_e32 v72, v64, v153
	v_max_f32_e32 v64, v69, v69
	v_max_f32_e32 v68, v68, v68
	v_max_f32_e32 v64, 0, v64
	v_mul_f32_e32 v69, v65, v153
	v_max_f32_e32 v65, v70, v70
	v_mul_f32_e32 v70, v66, v153
	v_max_f32_e32 v66, v71, v71
	v_max_f32_e32 v67, v67, v67
	v_max_f32_e32 v68, 0, v68
	v_mul_f32_e32 v64, v64, v64
	v_max_f32_e32 v65, 0, v65
	v_max_f32_e32 v66, 0, v66
	v_max_f32_e32 v67, 0, v67
	v_max_f32_e32 v56, v56, v56
	v_max_f32_e32 v57, v57, v57
	v_max_f32_e32 v58, v58, v58
	v_mul_f32_e32 v68, v68, v68
	v_mul_f32_e32 v64, v64, v153
	v_mul_f32_e32 v65, v65, v65
	v_mul_f32_e32 v66, v66, v66
	v_mul_f32_e32 v67, v67, v67
	v_max_f32_e32 v56, 0, v56
	v_max_f32_e32 v57, 0, v57
	v_max_f32_e32 v58, 0, v58
	v_mul_f32_e32 v68, v68, v153
	v_mul_f32_e32 v65, v65, v153
	v_mul_f32_e32 v66, v66, v153
	v_mul_f32_e32 v67, v67, v153
	v_cvt_pk_bf16_f32 v64, v68, v64
	v_mul_f32_e32 v56, v56, v56
	v_mul_f32_e32 v57, v57, v57
;     template <bool GATE> __device__ __forceinline__ void run(const f32x4 (&acc)[2][2][4][2], const Unit& u, int wr, int wc, int fr, int fq) const {
;     ...
;             for (int m = 0; m < 4; ++m) rsc[ai][m] = (MODE == EP_RELU2) ? __builtin_amdgcn_rcpf(RS[row0 + ai * HALF + m * 16] * (1.0f / 2048.0f) + 1e-6f) : 1.0f;
; #pragma unroll
;         for (int ai = 0; ai < 2; ++ai)
; #pragma unroll
;             for (int m = 0; m < 4; ++m) { const size_t r = (size_t)(row0 + ai * HALF + m * 16); float ss = 0.f;
; #pragma unroll
;                 for (int bj = 0; bj < 2; ++bj) { const int c = col0 + bj * HALF; f32x4 v0 = acc[ai][bj][m][0], v1 = acc[ai][bj][m][1];
;                     if (MODE == EP_INPROJ) { if (gate) { v0 = sigmoid4(v0 + bv[bj][0]); v1 = sigmoid4(v1 + bv[bj][1]); } }
;                     if (MODE == EP_T1 || MODE == EP_MERGE) { f32x4 g0, g1; unpack8(*(const u32x4*)(Gt + r * ldg + c), g0, g1); v0 = v0 * g0; v1 = v1 * g1; }
;                     if (MODE == EP_MERGE) { f32x4 t0, t1; unpack8(*(const u32x4*)(T + r * ldt + c), t0, t1); v0 = v0 + t0; v1 = v1 + t1; }
;                     if (MODE == EP_RELU2) {
; #pragma unroll
;                         for (int i = 0; i < 4; ++i) { const float a = fmaxf(v0[i], 0.f), b = fmaxf(v1[i], 0.f); v0[i] = a * a * rsc[ai][m]; v1[i] = b * b * rsc[ai][m]; } }
;                     if (MODE == EP_RESID_N) { const float* xp = X + r * 2048 + c; float* op = XO + r * 2048 + c;
;                         const f32x4 y0 = *(const f32x4*)xp + v0, y1 = *(const f32x4*)(xp + 4) + v1; *(f32x4*)op = y0; *(f32x4*)(op + 4) = y1;
;                         ss += (y0[0] * y0[0] + y0[1] * y0[1]) + (y0[2] * y0[2] + y0[3] * y0[3]) + (y1[0] * y1[0] + y1[1] * y1[1]) + (y1[2] * y1[2] + y1[3] * y1[3]);
;                         v0 = y0 * bv[bj][0]; v1 = y1 * bv[bj][1]; }
;                     if (MODE == EP_RESID) { const float* xp = X + r * 2048 + c; float* op = XO + r * 2048 + c;
;                         const f32x4 x0 = *(const f32x4*)xp, x1 = *(const f32x4*)(xp + 4); *(f32x4*)op = x0 + v0; *(f32x4*)(op + 4) = x1 + v1; }
;                     else { u32x4 w; w.x = cvt_pk_bf16(v0[0], v0[1]); w.y = cvt_pk_bf16(v0[2], v0[3]); w.z = cvt_pk_bf16(v1[0], v1[1]); w.w = cvt_pk_bf16(v1[2], v1[3]);
;                         *(u32x4*)(O + r * ldc + c) = w; } }
	v_mul_f32_e32 v58, v58, v58
	v_cvt_pk_bf16_f32 v65, v65, v66
	v_cvt_pk_bf16_f32 v66, v72, v69
	v_cvt_pk_bf16_f32 v67, v70, v67
	global_store_dwordx4 v[76:77], v[64:67], off offset:256 nt
	v_max_f32_e32 v60, v60, v60
	v_max_f32_e32 v60, 0, v60
	v_mul_f32_e32 v64, v56, v156
	v_max_f32_e32 v56, v61, v61
	v_mul_f32_e32 v61, v57, v156
	v_max_f32_e32 v57, v62, v62
	v_mul_f32_e32 v62, v58, v156
	v_max_f32_e32 v58, v63, v63
	v_max_f32_e32 v56, 0, v56
	v_max_f32_e32 v57, 0, v57
	v_max_f32_e32 v58, 0, v58
	v_max_f32_e32 v59, v59, v59
	v_mul_f32_e32 v60, v60, v60
	v_mul_f32_e32 v56, v56, v56
	v_mul_f32_e32 v57, v57, v57
	v_max_f32_e32 v59, 0, v59
	v_mul_f32_e32 v58, v58, v58
	v_mul_f32_e32 v60, v60, v156
	v_mul_f32_e32 v56, v56, v156
	v_mul_f32_e32 v57, v57, v156
	v_mul_f32_e32 v58, v58, v156
	v_mul_f32_e32 v59, v59, v59
	s_mov_b64 s[24:25], 0x200000
	v_mul_f32_e32 v59, v59, v156
	v_cvt_pk_bf16_f32 v56, v60, v56
	v_cvt_pk_bf16_f32 v57, v57, v58
	v_cvt_pk_bf16_f32 v58, v64, v61
	v_lshl_add_u64 v[60:61], v[112:113], 0, s[24:25]
	s_mov_b32 s24, 0x200000
	v_max_f32_e32 v48, v48, v48
	v_cvt_pk_bf16_f32 v59, v62, v59
	v_add_co_u32_e32 v62, vcc, s24, v112
	v_max_f32_e32 v48, 0, v48
	v_max_f32_e32 v49, v49, v49
	v_max_f32_e32 v50, v50, v50
	v_addc_co_u32_e32 v63, vcc, 0, v113, vcc
	v_mul_f32_e32 v48, v48, v48
	v_max_f32_e32 v49, 0, v49
	v_max_f32_e32 v50, 0, v50
	global_store_dwordx4 v[62:63], v[56:59], off nt
	v_mul_f32_e32 v49, v49, v49
	v_mul_f32_e32 v50, v50, v50
	v_mul_f32_e32 v56, v48, v156
	v_max_f32_e32 v48, v53, v53
	v_rcp_f32_e32 v122, v122
	v_max_f32_e32 v52, v52, v52
	v_max_f32_e32 v48, 0, v48
	v_mul_f32_e32 v53, v49, v156
	v_max_f32_e32 v49, v54, v54
	v_mul_f32_e32 v54, v50, v156
	v_max_f32_e32 v50, v55, v55
	v_max_f32_e32 v51, v51, v51
	v_max_f32_e32 v52, 0, v52
	v_mul_f32_e32 v48, v48, v48
	v_max_f32_e32 v49, 0, v49
	v_max_f32_e32 v50, 0, v50
	v_max_f32_e32 v51, 0, v51
	v_max_f32_e32 v40, v40, v40
	v_max_f32_e32 v41, v41, v41
	v_max_f32_e32 v42, v42, v42
	v_mul_f32_e32 v52, v52, v52
	v_mul_f32_e32 v48, v48, v156
	v_mul_f32_e32 v49, v49, v49
	v_mul_f32_e32 v50, v50, v50
	v_mul_f32_e32 v51, v51, v51
	v_max_f32_e32 v40, 0, v40
	v_max_f32_e32 v41, 0, v41
	v_max_f32_e32 v42, 0, v42
	v_mul_f32_e32 v52, v52, v156
	v_mul_f32_e32 v49, v49, v156
	v_mul_f32_e32 v50, v50, v156
	v_mul_f32_e32 v51, v51, v156
	v_cvt_pk_bf16_f32 v48, v52, v48
	v_mul_f32_e32 v40, v40, v40
	v_mul_f32_e32 v41, v41, v41
	v_mul_f32_e32 v42, v42, v42
	v_cvt_pk_bf16_f32 v49, v49, v50
	v_cvt_pk_bf16_f32 v50, v56, v53
	v_cvt_pk_bf16_f32 v51, v54, v51
	global_store_dwordx4 v[60:61], v[48:51], off offset:256 nt
	v_max_f32_e32 v44, v44, v44
	v_max_f32_e32 v44, 0, v44
	v_mul_f32_e32 v48, v40, v122
	v_max_f32_e32 v40, v45, v45
	v_mul_f32_e32 v45, v41, v122
	v_max_f32_e32 v41, v46, v46
	v_mul_f32_e32 v46, v42, v122
	v_max_f32_e32 v42, v47, v47
	v_max_f32_e32 v40, 0, v40
	v_max_f32_e32 v41, 0, v41
	v_max_f32_e32 v42, 0, v42
	v_max_f32_e32 v43, v43, v43
	v_mul_f32_e32 v44, v44, v44
	v_mul_f32_e32 v40, v40, v40
	v_mul_f32_e32 v41, v41, v41
	v_max_f32_e32 v43, 0, v43
	v_mul_f32_e32 v42, v42, v42
	v_mul_f32_e32 v44, v44, v122
	v_mul_f32_e32 v40, v40, v122
	v_mul_f32_e32 v41, v41, v122
	v_mul_f32_e32 v42, v42, v122
	v_mul_f32_e32 v43, v43, v43
	s_mov_b64 s[24:25], 0x240000
	v_mul_f32_e32 v43, v43, v122
	v_cvt_pk_bf16_f32 v40, v44, v40
	v_cvt_pk_bf16_f32 v41, v41, v42
	v_cvt_pk_bf16_f32 v42, v48, v45
	v_lshl_add_u64 v[44:45], v[112:113], 0, s[24:25]
	s_mov_b32 s24, 0x240000
	v_max_f32_e32 v32, v32, v32
	v_cvt_pk_bf16_f32 v43, v46, v43
	v_add_co_u32_e32 v46, vcc, s24, v112
	v_max_f32_e32 v32, 0, v32
	v_max_f32_e32 v33, v33, v33
	v_max_f32_e32 v34, v34, v34
	v_addc_co_u32_e32 v47, vcc, 0, v113, vcc
	v_mul_f32_e32 v32, v32, v32
	v_max_f32_e32 v33, 0, v33
	v_max_f32_e32 v34, 0, v34
	global_store_dwordx4 v[46:47], v[40:43], off nt
	v_mul_f32_e32 v33, v33, v33
	v_mul_f32_e32 v34, v34, v34
	v_mul_f32_e32 v40, v32, v122
	v_max_f32_e32 v32, v37, v37
	v_max_f32_e32 v36, v36, v36
	v_max_f32_e32 v32, 0, v32
	v_mul_f32_e32 v37, v33, v122
	v_max_f32_e32 v33, v38, v38
	v_mul_f32_e32 v38, v34, v122
	v_max_f32_e32 v34, v39, v39
	v_max_f32_e32 v35, v35, v35
	v_max_f32_e32 v36, 0, v36
	v_mul_f32_e32 v32, v32, v32
	v_max_f32_e32 v33, 0, v33
	v_max_f32_e32 v34, 0, v34
	v_max_f32_e32 v35, 0, v35
	v_max_f32_e32 v24, v24, v24
	v_max_f32_e32 v25, v25, v25
	v_max_f32_e32 v26, v26, v26
	v_mul_f32_e32 v36, v36, v36
	v_mul_f32_e32 v32, v32, v122
	v_mul_f32_e32 v33, v33, v33
	v_mul_f32_e32 v34, v34, v34
	v_mul_f32_e32 v35, v35, v35
	v_max_f32_e32 v24, 0, v24
	v_max_f32_e32 v25, 0, v25
	v_max_f32_e32 v26, 0, v26
	v_mul_f32_e32 v36, v36, v122
	v_mul_f32_e32 v33, v33, v122
	v_mul_f32_e32 v34, v34, v122
	v_mul_f32_e32 v35, v35, v122
	v_cvt_pk_bf16_f32 v32, v36, v32
	v_mul_f32_e32 v24, v24, v24
;     template <bool GATE> __device__ __forceinline__ void run(const f32x4 (&acc)[2][2][4][2], const Unit& u, int wr, int wc, int fr, int fq) const {
;     ...
;             for (int m = 0; m < 4; ++m) rsc[ai][m] = (MODE == EP_RELU2) ? __builtin_amdgcn_rcpf(RS[row0 + ai * HALF + m * 16] * (1.0f / 2048.0f) + 1e-6f) : 1.0f;
; #pragma unroll
;         for (int ai = 0; ai < 2; ++ai)
; #pragma unroll
;             for (int m = 0; m < 4; ++m) { const size_t r = (size_t)(row0 + ai * HALF + m * 16); float ss = 0.f;
; #pragma unroll
;                 for (int bj = 0; bj < 2; ++bj) { const int c = col0 + bj * HALF; f32x4 v0 = acc[ai][bj][m][0], v1 = acc[ai][bj][m][1];
;                     if (MODE == EP_INPROJ) { if (gate) { v0 = sigmoid4(v0 + bv[bj][0]); v1 = sigmoid4(v1 + bv[bj][1]); } }
;                     if (MODE == EP_T1 || MODE == EP_MERGE) { f32x4 g0, g1; unpack8(*(const u32x4*)(Gt + r * ldg + c), g0, g1); v0 = v0 * g0; v1 = v1 * g1; }
;                     if (MODE == EP_MERGE) { f32x4 t0, t1; unpack8(*(const u32x4*)(T + r * ldt + c), t0, t1); v0 = v0 + t0; v1 = v1 + t1; }
;                     if (MODE == EP_RELU2) {
; #pragma unroll
;                         for (int i = 0; i < 4; ++i) { const float a = fmaxf(v0[i], 0.f), b = fmaxf(v1[i], 0.f); v0[i] = a * a * rsc[ai][m]; v1[i] = b * b * rsc[ai][m]; } }
;                     if (MODE == EP_RESID_N) { const float* xp = X + r * 2048 + c; float* op = XO + r * 2048 + c;
;                         const f32x4 y0 = *(const f32x4*)xp + v0, y1 = *(const f32x4*)(xp + 4) + v1; *(f32x4*)op = y0; *(f32x4*)(op + 4) = y1;
;                         ss += (y0[0] * y0[0] + y0[1] * y0[1]) + (y0[2] * y0[2] + y0[3] * y0[3]) + (y1[0] * y1[0] + y1[1] * y1[1]) + (y1[2] * y1[2] + y1[3] * y1[3]);
;                         v0 = y0 * bv[bj][0]; v1 = y1 * bv[bj][1]; }
;                     if (MODE == EP_RESID) { const float* xp = X + r * 2048 + c; float* op = XO + r * 2048 + c;
;                         const f32x4 x0 = *(const f32x4*)xp, x1 = *(const f32x4*)(xp + 4); *(f32x4*)op = x0 + v0; *(f32x4*)(op + 4) = x1 + v1; }
;                     else { u32x4 w; w.x = cvt_pk_bf16(v0[0], v0[1]); w.y = cvt_pk_bf16(v0[2], v0[3]); w.z = cvt_pk_bf16(v1[0], v1[1]); w.w = cvt_pk_bf16(v1[2], v1[3]);
;                         *(u32x4*)(O + r * ldc + c) = w; } }
	v_mul_f32_e32 v25, v25, v25
	v_mul_f32_e32 v26, v26, v26
	v_cvt_pk_bf16_f32 v33, v33, v34
	v_cvt_pk_bf16_f32 v34, v40, v37
	v_cvt_pk_bf16_f32 v35, v38, v35
	global_store_dwordx4 v[44:45], v[32:35], off offset:256 nt
	v_max_f32_e32 v28, v28, v28
	v_max_f32_e32 v28, 0, v28
	v_mul_f32_e32 v32, v24, v121
	v_max_f32_e32 v24, v29, v29
	v_mul_f32_e32 v29, v25, v121
	v_max_f32_e32 v25, v30, v30
	v_mul_f32_e32 v30, v26, v121
	v_max_f32_e32 v26, v31, v31
	v_max_f32_e32 v24, 0, v24
	v_max_f32_e32 v25, 0, v25
	v_max_f32_e32 v26, 0, v26
	v_max_f32_e32 v27, v27, v27
	v_mul_f32_e32 v28, v28, v28
	v_mul_f32_e32 v24, v24, v24
	v_mul_f32_e32 v25, v25, v25
	v_max_f32_e32 v27, 0, v27
	v_mul_f32_e32 v26, v26, v26
	v_mul_f32_e32 v28, v28, v121
	v_mul_f32_e32 v24, v24, v121
	v_mul_f32_e32 v25, v25, v121
	v_mul_f32_e32 v26, v26, v121
	v_mul_f32_e32 v27, v27, v27
	s_mov_b64 s[24:25], 0x280000
	v_mul_f32_e32 v27, v27, v121
	v_cvt_pk_bf16_f32 v24, v28, v24
	v_cvt_pk_bf16_f32 v25, v25, v26
	v_cvt_pk_bf16_f32 v26, v32, v29
	v_lshl_add_u64 v[28:29], v[112:113], 0, s[24:25]
	s_mov_b32 s24, 0x280000
	v_max_f32_e32 v16, v16, v16
	v_cvt_pk_bf16_f32 v27, v30, v27
	v_add_co_u32_e32 v30, vcc, s24, v112
	v_max_f32_e32 v16, 0, v16
	v_max_f32_e32 v17, v17, v17
	v_max_f32_e32 v18, v18, v18
	v_addc_co_u32_e32 v31, vcc, 0, v113, vcc
	v_mul_f32_e32 v16, v16, v16
	v_max_f32_e32 v17, 0, v17
	v_max_f32_e32 v18, 0, v18
	global_store_dwordx4 v[30:31], v[24:27], off nt
	v_mul_f32_e32 v17, v17, v17
	v_mul_f32_e32 v18, v18, v18
	v_mul_f32_e32 v24, v16, v121
	v_max_f32_e32 v16, v21, v21
	v_max_f32_e32 v20, v20, v20
	v_max_f32_e32 v16, 0, v16
	v_mul_f32_e32 v21, v17, v121
	v_max_f32_e32 v17, v22, v22
	v_mul_f32_e32 v22, v18, v121
	v_max_f32_e32 v18, v23, v23
	v_max_f32_e32 v19, v19, v19
	v_max_f32_e32 v20, 0, v20
	v_mul_f32_e32 v16, v16, v16
	v_max_f32_e32 v17, 0, v17
	v_max_f32_e32 v18, 0, v18
	v_max_f32_e32 v19, 0, v19
	v_max_f32_e32 v8, v8, v8
	v_max_f32_e32 v9, v9, v9
	v_max_f32_e32 v10, v10, v10
	v_mul_f32_e32 v20, v20, v20
	v_mul_f32_e32 v16, v16, v121
	v_mul_f32_e32 v17, v17, v17
	v_mul_f32_e32 v18, v18, v18
	v_mul_f32_e32 v19, v19, v19
	v_max_f32_e32 v8, 0, v8
	v_max_f32_e32 v9, 0, v9
	v_max_f32_e32 v10, 0, v10
	v_mul_f32_e32 v20, v20, v121
	v_mul_f32_e32 v17, v17, v121
	v_mul_f32_e32 v18, v18, v121
	v_mul_f32_e32 v19, v19, v121
	v_cvt_pk_bf16_f32 v16, v20, v16
	v_mul_f32_e32 v8, v8, v8
	v_mul_f32_e32 v9, v9, v9
	v_mul_f32_e32 v10, v10, v10
	v_cvt_pk_bf16_f32 v17, v17, v18
	v_cvt_pk_bf16_f32 v18, v24, v21
	v_cvt_pk_bf16_f32 v19, v22, v19
	global_store_dwordx4 v[28:29], v[16:19], off offset:256 nt
	v_max_f32_e32 v12, v12, v12
	v_max_f32_e32 v12, 0, v12
	v_mul_f32_e32 v16, v8, v120
	v_max_f32_e32 v8, v13, v13
	v_mul_f32_e32 v13, v9, v120
	v_max_f32_e32 v9, v14, v14
	v_mul_f32_e32 v14, v10, v120
	v_max_f32_e32 v10, v15, v15
	v_max_f32_e32 v8, 0, v8
	v_max_f32_e32 v9, 0, v9
	v_max_f32_e32 v10, 0, v10
	v_max_f32_e32 v11, v11, v11
	v_mul_f32_e32 v12, v12, v12
	v_mul_f32_e32 v8, v8, v8
	v_mul_f32_e32 v9, v9, v9
	v_max_f32_e32 v11, 0, v11
	v_mul_f32_e32 v10, v10, v10
	v_mul_f32_e32 v12, v12, v120
	v_mul_f32_e32 v8, v8, v120
	v_mul_f32_e32 v9, v9, v120
	v_mul_f32_e32 v10, v10, v120
	v_mul_f32_e32 v11, v11, v11
	s_mov_b64 s[24:25], 0x2c0000
	v_mul_f32_e32 v11, v11, v120
	v_cvt_pk_bf16_f32 v8, v12, v8
	v_cvt_pk_bf16_f32 v9, v9, v10
	v_cvt_pk_bf16_f32 v10, v16, v13
	v_lshl_add_u64 v[12:13], v[112:113], 0, s[24:25]
	s_mov_b32 s24, 0x2c0000
	v_max_f32_e32 v0, v0, v0
	v_max_f32_e32 v1, v1, v1
	v_max_f32_e32 v2, v2, v2
	v_cvt_pk_bf16_f32 v11, v14, v11
	v_add_co_u32_e32 v14, vcc, s24, v112
	v_max_f32_e32 v0, 0, v0
	v_max_f32_e32 v1, 0, v1
	v_max_f32_e32 v2, 0, v2
	v_addc_co_u32_e32 v15, vcc, 0, v113, vcc
	v_mul_f32_e32 v0, v0, v0
	v_mul_f32_e32 v1, v1, v1
	v_mul_f32_e32 v2, v2, v2
	global_store_dwordx4 v[14:15], v[8:11], off nt
	v_max_f32_e32 v3, v3, v3
	v_max_f32_e32 v4, v4, v4
	v_mul_f32_e32 v8, v0, v120
	v_max_f32_e32 v0, v5, v5
	v_mul_f32_e32 v5, v1, v120
	v_max_f32_e32 v1, v6, v6
	v_mul_f32_e32 v6, v2, v120
	v_max_f32_e32 v2, v7, v7
	v_max_f32_e32 v0, 0, v0
	v_max_f32_e32 v1, 0, v1
	v_max_f32_e32 v2, 0, v2
	v_max_f32_e32 v3, 0, v3
	v_max_f32_e32 v4, 0, v4
	v_mul_f32_e32 v0, v0, v0
	v_mul_f32_e32 v1, v1, v1
	v_mul_f32_e32 v2, v2, v2
	v_mul_f32_e32 v3, v3, v3
	v_mul_f32_e32 v4, v4, v4
	v_mul_f32_e32 v0, v0, v120
	v_mul_f32_e32 v1, v1, v120
	v_mul_f32_e32 v2, v2, v120
	v_mul_f32_e32 v3, v3, v120
	s_andn2_b64 vcc, exec, s[42:43]
	s_mov_b64 s[42:43], -1
	v_mul_f32_e32 v4, v4, v120
	v_cvt_pk_bf16_f32 v0, v4, v0
	v_cvt_pk_bf16_f32 v1, v1, v2
	v_cvt_pk_bf16_f32 v2, v8, v5
	v_cvt_pk_bf16_f32 v3, v6, v3
	global_store_dwordx4 v[12:13], v[0:3], off offset:256 nt
	s_cbranch_vccnz .LBB0_764
	s_andn2_b64 vcc, exec, s[14:15]
	s_cbranch_vccnz .LBB0_763
	s_barrier
	s_branch .LBB0_763
